# P6 EpiDown: y loads/stores re-laid out by DPP row_ror:8 so each instruction covers 8 rows x 128B full lines; 5 rows in flight
# speedup vs baseline: 1.0183x; 1.0039x over previous
; #define PG8_STAGE(bufoff, gbase, voff) do { _Pragma("unroll") for (int _i = 0; _i < 2; ++_i) \
;         __builtin_amdgcn_global_load_lds((const unsigned*)((const char*)(gbase) + (voff)[_i]), (PG8_LAS unsigned*)(lds + (bufoff) + ldsw + _i * 8192), 16, 0, 0); } while (0)
; #define PG8_LDA(dst, b, h) do { _Pragma("unroll") for (int m = 0; m < 4; ++m) _Pragma("unroll") for (int k = 0; k < 2; ++k) dst[m][k] = *(const PG8_LAS bf16x8*)(lds + PG8_SA(b, h) + aoff + m * 2048 + k * 1024); } while (0)
; #define PG8_LDB(dst, b, h) do { _Pragma("unroll") for (int n = 0; n < 2; ++n) _Pragma("unroll") for (int k = 0; k < 2; ++k) dst[n][k] = *(const PG8_LAS bf16x8*)(lds + PG8_SB(b, h) + boff + n * 2048 + k * 1024); } while (0)
; #define PG8_MMA(ai, bj, At, Bt) do { __builtin_amdgcn_s_setprio(1); _Pragma("unroll") for (int m = 0; m < 4; ++m) _Pragma("unroll") for (int n = 0; n < 2; ++n) _Pragma("unroll") for (int k = 0; k < 2; ++k) \
;         acc[ai][bj][m][n] = __builtin_amdgcn_mfma_f32_16x16x32_bf16(Bt[n][k], At[m][k], acc[ai][bj][m][n], 0, 0, 0); __builtin_amdgcn_s_setprio(0); } while (0)
; #define PG8_WAIT_V(n) asm volatile("s_waitcnt vmcnt(" #n ")" ::: "memory")
; #define PG8_WAIT_L(n) asm volatile("s_waitcnt lgkmcnt(" #n ")" ::: "memory")
; #define PG8_BAR __builtin_amdgcn_s_barrier()
; #define PG8_SCHED __builtin_amdgcn_sched_barrier(0)
; template <class Epi, class Sched, bool ALIGN_EPI = false, bool SP2 = false>
; __device__ __forceinline__ void gemm_phase(PG8_LAS unsigned char* lds, const Gemm g, const Sched& S, const Epi& E) {
;     ...
;             PG8_LDB(B0, 0, 0); PG8_LDB(B1, 0, 1); PG8_SCHED; PG8_LDA(At, 0, 0); PG8_STAGE(PG8_SA(1, 1), a1 + hstep, voffA);
;             PG8_WAIT_V(8); PG8_WAIT_L(0); PG8_BAR; PG8_MMA(0, 0, At, B0); PG8_MMA(0, 1, At, B1); PG8_BAR; PG8_SCHED;
;             PG8_LDA(At, 0, 1); PG8_STAGE(PG8_SB(0, 0), b2, voffB); PG8_STAGE(PG8_SB(0, 1), b2 + hstep, voffB); PG8_STAGE(PG8_SA(0, 0), a2, voffA);
;             PG8_WAIT_V(8); PG8_WAIT_L(0); PG8_BAR; PG8_MMA(1, 0, At, B0); PG8_MMA(1, 1, At, B1); PG8_BAR; PG8_SCHED;
.LBB0_1540:
	ds_read_b128 v[144:147], v151
	ds_read_b128 v[156:159], v151 offset:1024
	ds_read_b128 v[160:163], v151 offset:2048
	ds_read_b128 v[164:167], v151 offset:3072
	ds_read_b128 v[168:171], v152
	ds_read_b128 v[172:175], v152 offset:1024
	ds_read_b128 v[176:179], v152 offset:2048
	ds_read_b128 v[180:183], v152 offset:3072
	s_add_u32 s34, s30, 0xfffc0080
	s_addc_u32 s35, s31, -1
	s_cmp_eq_u32 s65, 12
	s_cselect_b32 s37, s23, s35
	s_cselect_b32 s36, s61, s34
	s_cselect_b32 s35, s19, s64
	s_cselect_b32 s34, s62, s63
	v_lshl_add_u64 v[216:217], s[30:31], 0, v[136:137]
	s_add_i32 m0, s29, 0xc000
	ds_read_b128 v[184:187], v153
	ds_read_b128 v[188:191], v153 offset:1024
	ds_read_b128 v[192:195], v153 offset:2048
	ds_read_b128 v[196:199], v153 offset:3072
	ds_read_b128 v[200:203], v153 offset:4096
	ds_read_b128 v[204:207], v153 offset:5120
	ds_read_b128 v[208:211], v153 offset:6144
	ds_read_b128 v[212:215], v153 offset:7168
	global_load_lds_dwordx4 v[216:217], off
	v_lshl_add_u64 v[216:217], s[30:31], 0, v[138:139]
	s_add_i32 m0, s29, 0xe000
	s_nop 0
	global_load_lds_dwordx4 v[216:217], off
	s_waitcnt vmcnt(8)
	s_waitcnt lgkmcnt(0)
	s_barrier
	s_setprio 1
	s_waitcnt lgkmcnt(0)
	v_mfma_f32_16x16x32_bf16 v[124:127], v[144:147], v[184:187], v[124:127]
	v_mfma_f32_16x16x32_bf16 v[120:123], v[160:163], v[184:187], v[120:123]
	v_mfma_f32_16x16x32_bf16 v[108:111], v[144:147], v[192:195], v[108:111]
	v_mfma_f32_16x16x32_bf16 v[104:107], v[160:163], v[192:195], v[104:107]
	v_mfma_f32_16x16x32_bf16 v[92:95], v[144:147], v[200:203], v[92:95]
	v_mfma_f32_16x16x32_bf16 v[88:91], v[160:163], v[200:203], v[88:91]
	v_mfma_f32_16x16x32_bf16 v[76:79], v[144:147], v[208:211], v[76:79]
	v_mfma_f32_16x16x32_bf16 v[72:75], v[160:163], v[208:211], v[72:75]
	v_mfma_f32_16x16x32_bf16 v[124:127], v[156:159], v[188:191], v[124:127]
	v_mfma_f32_16x16x32_bf16 v[120:123], v[164:167], v[188:191], v[120:123]
	v_mfma_f32_16x16x32_bf16 v[108:111], v[156:159], v[196:199], v[108:111]
	v_mfma_f32_16x16x32_bf16 v[104:107], v[164:167], v[196:199], v[104:107]
	v_mfma_f32_16x16x32_bf16 v[92:95], v[156:159], v[204:207], v[92:95]
	v_mfma_f32_16x16x32_bf16 v[88:91], v[164:167], v[204:207], v[88:91]
	v_mfma_f32_16x16x32_bf16 v[76:79], v[156:159], v[212:215], v[76:79]
	v_mfma_f32_16x16x32_bf16 v[72:75], v[164:167], v[212:215], v[72:75]
	s_setprio 0
	s_setprio 1
	v_mfma_f32_16x16x32_bf16 v[116:119], v[168:171], v[184:187], v[116:119]
	v_mfma_f32_16x16x32_bf16 v[112:115], v[176:179], v[184:187], v[112:115]
	v_mfma_f32_16x16x32_bf16 v[100:103], v[168:171], v[192:195], v[100:103]
	v_mfma_f32_16x16x32_bf16 v[96:99], v[176:179], v[192:195], v[96:99]
	v_mfma_f32_16x16x32_bf16 v[84:87], v[168:171], v[200:203], v[84:87]
	v_mfma_f32_16x16x32_bf16 v[80:83], v[176:179], v[200:203], v[80:83]
	v_mfma_f32_16x16x32_bf16 v[68:71], v[168:171], v[208:211], v[68:71]
	v_mfma_f32_16x16x32_bf16 v[64:67], v[176:179], v[208:211], v[64:67]
	v_mfma_f32_16x16x32_bf16 v[116:119], v[172:175], v[188:191], v[116:119]
	v_mfma_f32_16x16x32_bf16 v[112:115], v[180:183], v[188:191], v[112:115]
	v_mfma_f32_16x16x32_bf16 v[100:103], v[172:175], v[196:199], v[100:103]
	v_mfma_f32_16x16x32_bf16 v[96:99], v[180:183], v[196:199], v[96:99]
	v_mfma_f32_16x16x32_bf16 v[84:87], v[172:175], v[204:207], v[84:87]
	v_mfma_f32_16x16x32_bf16 v[80:83], v[180:183], v[204:207], v[80:83]
	v_mfma_f32_16x16x32_bf16 v[68:71], v[172:175], v[212:215], v[68:71]
	v_mfma_f32_16x16x32_bf16 v[64:67], v[180:183], v[212:215], v[64:67]
	s_setprio 0
	s_barrier
	s_add_i32 s66, s52, s39
	v_lshl_add_u64 v[216:217], s[34:35], 0, v[132:133]
	s_mov_b32 m0, s66
	ds_read_b128 v[184:187], v153 offset:16384
	ds_read_b128 v[188:191], v153 offset:17408
	ds_read_b128 v[192:195], v153 offset:18432
	ds_read_b128 v[196:199], v153 offset:19456
	ds_read_b128 v[200:203], v153 offset:20480
	ds_read_b128 v[204:207], v153 offset:21504
	ds_read_b128 v[208:211], v153 offset:22528
	ds_read_b128 v[212:215], v153 offset:23552
	global_load_lds_dwordx4 v[216:217], off
	s_add_i32 m0, s66, 0x2000
	s_add_u32 s66, s34, 0x40000
	v_lshl_add_u64 v[218:219], s[34:35], 0, v[128:129]
	s_addc_u32 s67, s35, 0
	s_add_i32 s68, s53, s39
	global_load_lds_dwordx4 v[218:219], off
	v_lshl_add_u64 v[220:221], s[66:67], 0, v[132:133]
	s_mov_b32 m0, s68
	v_lshl_add_u64 v[222:223], s[36:37], 0, v[130:131]
	global_load_lds_dwordx4 v[220:221], off
	v_lshl_add_u64 v[220:221], s[66:67], 0, v[128:129]
	s_add_i32 m0, s68, 0x2000
	s_nop 0
	global_load_lds_dwordx4 v[220:221], off
	v_lshl_add_u64 v[220:221], s[36:37], 0, v[134:135]
	s_mov_b32 m0, s29
	s_nop 0
	global_load_lds_dwordx4 v[220:221], off
	s_mov_b32 m0, s42
	s_nop 0
	global_load_lds_dwordx4 v[222:223], off
	s_waitcnt vmcnt(8)
	s_waitcnt lgkmcnt(0)
	s_barrier
; #define PG8_STAGE(bufoff, gbase, voff) do { _Pragma("unroll") for (int _i = 0; _i < 2; ++_i) \
;         __builtin_amdgcn_global_load_lds((const unsigned*)((const char*)(gbase) + (voff)[_i]), (PG8_LAS unsigned*)(lds + (bufoff) + ldsw + _i * 8192), 16, 0, 0); } while (0)
; #define PG8_LDA(dst, b, h) do { _Pragma("unroll") for (int m = 0; m < 4; ++m) _Pragma("unroll") for (int k = 0; k < 2; ++k) dst[m][k] = *(const PG8_LAS bf16x8*)(lds + PG8_SA(b, h) + aoff + m * 2048 + k * 1024); } while (0)
; #define PG8_LDB(dst, b, h) do { _Pragma("unroll") for (int n = 0; n < 2; ++n) _Pragma("unroll") for (int k = 0; k < 2; ++k) dst[n][k] = *(const PG8_LAS bf16x8*)(lds + PG8_SB(b, h) + boff + n * 2048 + k * 1024); } while (0)
; #define PG8_MMA(ai, bj, At, Bt) do { __builtin_amdgcn_s_setprio(1); _Pragma("unroll") for (int m = 0; m < 4; ++m) _Pragma("unroll") for (int n = 0; n < 2; ++n) _Pragma("unroll") for (int k = 0; k < 2; ++k) \
;         acc[ai][bj][m][n] = __builtin_amdgcn_mfma_f32_16x16x32_bf16(Bt[n][k], At[m][k], acc[ai][bj][m][n], 0, 0, 0); __builtin_amdgcn_s_setprio(0); } while (0)
; #define PG8_WAIT_V(n) asm volatile("s_waitcnt vmcnt(" #n ")" ::: "memory")
; #define PG8_WAIT_L(n) asm volatile("s_waitcnt lgkmcnt(" #n ")" ::: "memory")
; #define PG8_BAR __builtin_amdgcn_s_barrier()
; #define PG8_SCHED __builtin_amdgcn_sched_barrier(0)
; template <class Epi, class Sched, bool ALIGN_EPI = false, bool SP2 = false>
; __device__ __forceinline__ void gemm_phase(PG8_LAS unsigned char* lds, const Gemm g, const Sched& S, const Epi& E) {
;     ...
;             PG8_WAIT_V(8); PG8_WAIT_L(0); PG8_BAR; PG8_MMA(1, 0, At, B0); PG8_MMA(1, 1, At, B1); PG8_BAR; PG8_SCHED;
;             PG8_LDB(B0, 1, 0); PG8_LDB(B1, 1, 1); PG8_SCHED; PG8_LDA(At, 1, 0); PG8_STAGE(PG8_SA(0, 1), a2 + hstep, voffA);
;             PG8_WAIT_V(8); PG8_WAIT_L(0); PG8_BAR; PG8_MMA(0, 0, At, B0); PG8_MMA(0, 1, At, B1); PG8_BAR; PG8_SCHED;
	s_setprio 1
	s_waitcnt lgkmcnt(0)
	v_mfma_f32_16x16x32_bf16 v[60:63], v[144:147], v[184:187], v[60:63]
	v_mfma_f32_16x16x32_bf16 v[56:59], v[160:163], v[184:187], v[56:59]
	v_mfma_f32_16x16x32_bf16 v[44:47], v[144:147], v[192:195], v[44:47]
	v_mfma_f32_16x16x32_bf16 v[40:43], v[160:163], v[192:195], v[40:43]
	v_mfma_f32_16x16x32_bf16 v[28:31], v[144:147], v[200:203], v[28:31]
	v_mfma_f32_16x16x32_bf16 v[24:27], v[160:163], v[200:203], v[24:27]
	v_mfma_f32_16x16x32_bf16 v[12:15], v[144:147], v[208:211], v[12:15]
	v_mfma_f32_16x16x32_bf16 v[8:11], v[160:163], v[208:211], v[8:11]
	v_mfma_f32_16x16x32_bf16 v[60:63], v[156:159], v[188:191], v[60:63]
	v_mfma_f32_16x16x32_bf16 v[56:59], v[164:167], v[188:191], v[56:59]
	v_mfma_f32_16x16x32_bf16 v[44:47], v[156:159], v[196:199], v[44:47]
	v_mfma_f32_16x16x32_bf16 v[40:43], v[164:167], v[196:199], v[40:43]
	v_mfma_f32_16x16x32_bf16 v[28:31], v[156:159], v[204:207], v[28:31]
	v_mfma_f32_16x16x32_bf16 v[24:27], v[164:167], v[204:207], v[24:27]
	v_mfma_f32_16x16x32_bf16 v[12:15], v[156:159], v[212:215], v[12:15]
	v_mfma_f32_16x16x32_bf16 v[8:11], v[164:167], v[212:215], v[8:11]
	s_setprio 0
	s_setprio 1
	v_mfma_f32_16x16x32_bf16 v[52:55], v[168:171], v[184:187], v[52:55]
	v_mfma_f32_16x16x32_bf16 v[48:51], v[176:179], v[184:187], v[48:51]
	v_mfma_f32_16x16x32_bf16 v[36:39], v[168:171], v[192:195], v[36:39]
	v_mfma_f32_16x16x32_bf16 v[32:35], v[176:179], v[192:195], v[32:35]
	v_mfma_f32_16x16x32_bf16 v[20:23], v[168:171], v[200:203], v[20:23]
	v_mfma_f32_16x16x32_bf16 v[16:19], v[176:179], v[200:203], v[16:19]
	v_mfma_f32_16x16x32_bf16 v[4:7], v[168:171], v[208:211], v[4:7]
	v_mfma_f32_16x16x32_bf16 v[0:3], v[176:179], v[208:211], v[0:3]
	v_mfma_f32_16x16x32_bf16 v[52:55], v[172:175], v[188:191], v[52:55]
	v_mfma_f32_16x16x32_bf16 v[48:51], v[180:183], v[188:191], v[48:51]
	v_mfma_f32_16x16x32_bf16 v[36:39], v[172:175], v[196:199], v[36:39]
	v_mfma_f32_16x16x32_bf16 v[32:35], v[180:183], v[196:199], v[32:35]
	v_mfma_f32_16x16x32_bf16 v[20:23], v[172:175], v[204:207], v[20:23]
	v_mfma_f32_16x16x32_bf16 v[16:19], v[180:183], v[204:207], v[16:19]
	v_mfma_f32_16x16x32_bf16 v[4:7], v[172:175], v[212:215], v[4:7]
	v_mfma_f32_16x16x32_bf16 v[0:3], v[180:183], v[212:215], v[0:3]
	s_setprio 0
	s_barrier
	s_add_i32 s66, 0, 0x18000
	v_add_u32_e32 v155, s66, v149
	s_add_i32 s67, 0, 0x1c000
	ds_read_b128 v[144:147], v155
	ds_read_b128 v[156:159], v155 offset:1024
	ds_read_b128 v[160:163], v155 offset:2048
	ds_read_b128 v[164:167], v155 offset:3072
	v_add_u32_e32 v155, s67, v149
	ds_read_b128 v[168:171], v155
	ds_read_b128 v[172:175], v155 offset:1024
	ds_read_b128 v[176:179], v155 offset:2048
	ds_read_b128 v[180:183], v155 offset:3072
	s_add_u32 s36, s36, 0x40000
	s_addc_u32 s37, s37, 0
	s_mov_b32 m0, s43
	v_lshl_add_u64 v[224:225], s[36:37], 0, v[134:135]
	ds_read_b128 v[184:187], v153 offset:32768
	ds_read_b128 v[188:191], v153 offset:33792
	ds_read_b128 v[192:195], v153 offset:34816
	ds_read_b128 v[196:199], v153 offset:35840
	ds_read_b128 v[200:203], v153 offset:36864
	ds_read_b128 v[204:207], v153 offset:37888
	ds_read_b128 v[208:211], v153 offset:38912
	ds_read_b128 v[212:215], v153 offset:39936
	global_load_lds_dwordx4 v[224:225], off
	v_lshl_add_u64 v[224:225], s[36:37], 0, v[130:131]
	s_mov_b32 m0, s46
	s_nop 0
	global_load_lds_dwordx4 v[224:225], off
	s_waitcnt vmcnt(8)
	s_waitcnt lgkmcnt(0)
	s_barrier
	s_setprio 1
	s_waitcnt lgkmcnt(0)
	v_mfma_f32_16x16x32_bf16 v[124:127], v[144:147], v[184:187], v[124:127]
	v_mfma_f32_16x16x32_bf16 v[120:123], v[160:163], v[184:187], v[120:123]
	v_mfma_f32_16x16x32_bf16 v[108:111], v[144:147], v[192:195], v[108:111]
	v_mfma_f32_16x16x32_bf16 v[104:107], v[160:163], v[192:195], v[104:107]
	v_mfma_f32_16x16x32_bf16 v[92:95], v[144:147], v[200:203], v[92:95]
	v_mfma_f32_16x16x32_bf16 v[88:91], v[160:163], v[200:203], v[88:91]
	v_mfma_f32_16x16x32_bf16 v[76:79], v[144:147], v[208:211], v[76:79]
	v_mfma_f32_16x16x32_bf16 v[72:75], v[160:163], v[208:211], v[72:75]
	v_mfma_f32_16x16x32_bf16 v[124:127], v[156:159], v[188:191], v[124:127]
	v_mfma_f32_16x16x32_bf16 v[120:123], v[164:167], v[188:191], v[120:123]
	v_mfma_f32_16x16x32_bf16 v[108:111], v[156:159], v[196:199], v[108:111]
	v_mfma_f32_16x16x32_bf16 v[104:107], v[164:167], v[196:199], v[104:107]
	v_mfma_f32_16x16x32_bf16 v[92:95], v[156:159], v[204:207], v[92:95]
	v_mfma_f32_16x16x32_bf16 v[88:91], v[164:167], v[204:207], v[88:91]
	v_mfma_f32_16x16x32_bf16 v[76:79], v[156:159], v[212:215], v[76:79]
	v_mfma_f32_16x16x32_bf16 v[72:75], v[164:167], v[212:215], v[72:75]
	s_setprio 0
	s_setprio 1
	v_mfma_f32_16x16x32_bf16 v[116:119], v[168:171], v[184:187], v[116:119]
	v_mfma_f32_16x16x32_bf16 v[112:115], v[176:179], v[184:187], v[112:115]
	v_mfma_f32_16x16x32_bf16 v[100:103], v[168:171], v[192:195], v[100:103]
	v_mfma_f32_16x16x32_bf16 v[96:99], v[176:179], v[192:195], v[96:99]
	v_mfma_f32_16x16x32_bf16 v[84:87], v[168:171], v[200:203], v[84:87]
	v_mfma_f32_16x16x32_bf16 v[80:83], v[176:179], v[200:203], v[80:83]
	v_mfma_f32_16x16x32_bf16 v[68:71], v[168:171], v[208:211], v[68:71]
	v_mfma_f32_16x16x32_bf16 v[64:67], v[176:179], v[208:211], v[64:67]
	v_mfma_f32_16x16x32_bf16 v[116:119], v[172:175], v[188:191], v[116:119]
	v_mfma_f32_16x16x32_bf16 v[112:115], v[180:183], v[188:191], v[112:115]
	v_mfma_f32_16x16x32_bf16 v[100:103], v[172:175], v[196:199], v[100:103]
	v_mfma_f32_16x16x32_bf16 v[96:99], v[180:183], v[196:199], v[96:99]
	v_mfma_f32_16x16x32_bf16 v[84:87], v[172:175], v[204:207], v[84:87]
	v_mfma_f32_16x16x32_bf16 v[80:83], v[180:183], v[204:207], v[80:83]
	v_mfma_f32_16x16x32_bf16 v[68:71], v[172:175], v[212:215], v[68:71]
	v_mfma_f32_16x16x32_bf16 v[64:67], v[180:183], v[212:215], v[64:67]
	s_setprio 0
	s_barrier
; #define PG8_STAGE(bufoff, gbase, voff) do { _Pragma("unroll") for (int _i = 0; _i < 2; ++_i) \
;         __builtin_amdgcn_global_load_lds((const unsigned*)((const char*)(gbase) + (voff)[_i]), (PG8_LAS unsigned*)(lds + (bufoff) + ldsw + _i * 8192), 16, 0, 0); } while (0)
; #define PG8_LDA(dst, b, h) do { _Pragma("unroll") for (int m = 0; m < 4; ++m) _Pragma("unroll") for (int k = 0; k < 2; ++k) dst[m][k] = *(const PG8_LAS bf16x8*)(lds + PG8_SA(b, h) + aoff + m * 2048 + k * 1024); } while (0)
; #define PG8_MMA(ai, bj, At, Bt) do { __builtin_amdgcn_s_setprio(1); _Pragma("unroll") for (int m = 0; m < 4; ++m) _Pragma("unroll") for (int n = 0; n < 2; ++n) _Pragma("unroll") for (int k = 0; k < 2; ++k) \
;         acc[ai][bj][m][n] = __builtin_amdgcn_mfma_f32_16x16x32_bf16(Bt[n][k], At[m][k], acc[ai][bj][m][n], 0, 0, 0); __builtin_amdgcn_s_setprio(0); } while (0)
; #define PG8_WAIT_V(n) asm volatile("s_waitcnt vmcnt(" #n ")" ::: "memory")
; #define PG8_WAIT_L(n) asm volatile("s_waitcnt lgkmcnt(" #n ")" ::: "memory")
; #define PG8_BAR __builtin_amdgcn_s_barrier()
; #define PG8_SCHED __builtin_amdgcn_sched_barrier(0)
; template <class Epi, class Sched, bool ALIGN_EPI = false, bool SP2 = false>
; __device__ __forceinline__ void gemm_phase(PG8_LAS unsigned char* lds, const Gemm g, const Sched& S, const Epi& E) {
;     ...
;             PG8_LDA(At, 1, 1); PG8_STAGE(PG8_SB(1, 0), b3, voffB); PG8_STAGE(PG8_SB(1, 1), b3 + hstep, voffB); PG8_STAGE(PG8_SA(1, 0), a3, voffA);
;             PG8_WAIT_V(8); PG8_WAIT_L(0); PG8_BAR; PG8_MMA(1, 0, At, B0); PG8_MMA(1, 1, At, B1); PG8_BAR; PG8_SCHED;
;     ...
;         if constexpr (ALIGN_EPI) { if (wr == 0) PG8_BAR; }
	s_add_i32 s36, s66, s39
	v_lshl_add_u64 v[216:217], v[216:217], 0, s[14:15]
	s_mov_b32 m0, s36
	ds_read_b128 v[184:187], v153 offset:49152
	ds_read_b128 v[188:191], v153 offset:50176
	ds_read_b128 v[192:195], v153 offset:51200
	ds_read_b128 v[196:199], v153 offset:52224
	ds_read_b128 v[200:203], v153 offset:53248
	ds_read_b128 v[204:207], v153 offset:54272
	ds_read_b128 v[208:211], v153 offset:55296
	ds_read_b128 v[212:215], v153 offset:56320
	global_load_lds_dwordx4 v[216:217], off
	s_add_i32 m0, s36, 0x2000
	s_add_u32 s34, s34, 0x40080
	v_lshl_add_u64 v[216:217], v[218:219], 0, s[14:15]
	s_addc_u32 s35, s35, 0
	s_add_i32 s36, s67, s39
	global_load_lds_dwordx4 v[216:217], off
	v_lshl_add_u64 v[216:217], s[34:35], 0, v[132:133]
	s_mov_b32 m0, s36
	s_nop 0
	global_load_lds_dwordx4 v[216:217], off
	v_lshl_add_u64 v[216:217], s[34:35], 0, v[128:129]
	s_add_i32 m0, s36, 0x2000
	s_nop 0
	global_load_lds_dwordx4 v[216:217], off
	v_lshl_add_u64 v[216:217], v[220:221], 0, s[14:15]
	s_mov_b32 m0, s49
	s_nop 0
	global_load_lds_dwordx4 v[216:217], off
	v_lshl_add_u64 v[216:217], v[222:223], 0, s[14:15]
	s_mov_b32 m0, s50
	s_nop 0
	global_load_lds_dwordx4 v[216:217], off
	s_waitcnt vmcnt(8)
	s_waitcnt lgkmcnt(0)
	s_barrier
	s_setprio 1
	s_waitcnt lgkmcnt(0)
	v_mfma_f32_16x16x32_bf16 v[60:63], v[144:147], v[184:187], v[60:63]
	v_mfma_f32_16x16x32_bf16 v[56:59], v[160:163], v[184:187], v[56:59]
	v_mfma_f32_16x16x32_bf16 v[44:47], v[144:147], v[192:195], v[44:47]
	v_mfma_f32_16x16x32_bf16 v[40:43], v[160:163], v[192:195], v[40:43]
	v_mfma_f32_16x16x32_bf16 v[28:31], v[144:147], v[200:203], v[28:31]
	v_mfma_f32_16x16x32_bf16 v[24:27], v[160:163], v[200:203], v[24:27]
	v_mfma_f32_16x16x32_bf16 v[12:15], v[144:147], v[208:211], v[12:15]
	v_mfma_f32_16x16x32_bf16 v[8:11], v[160:163], v[208:211], v[8:11]
	v_mfma_f32_16x16x32_bf16 v[60:63], v[156:159], v[188:191], v[60:63]
	v_mfma_f32_16x16x32_bf16 v[56:59], v[164:167], v[188:191], v[56:59]
	v_mfma_f32_16x16x32_bf16 v[44:47], v[156:159], v[196:199], v[44:47]
	v_mfma_f32_16x16x32_bf16 v[40:43], v[164:167], v[196:199], v[40:43]
	v_mfma_f32_16x16x32_bf16 v[28:31], v[156:159], v[204:207], v[28:31]
	v_mfma_f32_16x16x32_bf16 v[24:27], v[164:167], v[204:207], v[24:27]
	v_mfma_f32_16x16x32_bf16 v[12:15], v[156:159], v[212:215], v[12:15]
	v_mfma_f32_16x16x32_bf16 v[8:11], v[164:167], v[212:215], v[8:11]
	s_setprio 0
	s_setprio 1
	v_mfma_f32_16x16x32_bf16 v[52:55], v[168:171], v[184:187], v[52:55]
	v_mfma_f32_16x16x32_bf16 v[48:51], v[176:179], v[184:187], v[48:51]
	v_mfma_f32_16x16x32_bf16 v[36:39], v[168:171], v[192:195], v[36:39]
	v_mfma_f32_16x16x32_bf16 v[32:35], v[176:179], v[192:195], v[32:35]
	v_mfma_f32_16x16x32_bf16 v[20:23], v[168:171], v[200:203], v[20:23]
	v_mfma_f32_16x16x32_bf16 v[16:19], v[176:179], v[200:203], v[16:19]
	v_mfma_f32_16x16x32_bf16 v[4:7], v[168:171], v[208:211], v[4:7]
	v_mfma_f32_16x16x32_bf16 v[0:3], v[176:179], v[208:211], v[0:3]
	v_mfma_f32_16x16x32_bf16 v[52:55], v[172:175], v[188:191], v[52:55]
	v_mfma_f32_16x16x32_bf16 v[48:51], v[180:183], v[188:191], v[48:51]
	v_mfma_f32_16x16x32_bf16 v[36:39], v[172:175], v[196:199], v[36:39]
	v_mfma_f32_16x16x32_bf16 v[32:35], v[180:183], v[196:199], v[32:35]
	v_mfma_f32_16x16x32_bf16 v[20:23], v[172:175], v[204:207], v[20:23]
	v_mfma_f32_16x16x32_bf16 v[16:19], v[180:183], v[204:207], v[16:19]
	v_mfma_f32_16x16x32_bf16 v[4:7], v[172:175], v[212:215], v[4:7]
	v_mfma_f32_16x16x32_bf16 v[0:3], v[180:183], v[212:215], v[0:3]
	s_setprio 0
	s_barrier
	s_add_i32 s65, s65, 2
	s_add_u32 s30, s30, 0x100
	s_addc_u32 s31, s31, 0
	s_add_u32 s63, s63, 0x100
	s_addc_u32 s64, s64, 0
	s_cmp_gt_u32 s65, 13
	s_cbranch_scc0 .LBB0_1540
	s_and_b64 vcc, exec, s[16:17]
	s_cbranch_vccz .LBB0_1543
	s_barrier

; #define PG8_STAGE(bufoff, gbase, voff) do { _Pragma("unroll") for (int _i = 0; _i < 2; ++_i) \
;         __builtin_amdgcn_global_load_lds((const unsigned*)((const char*)(gbase) + (voff)[_i]), (PG8_LAS unsigned*)(lds + (bufoff) + ldsw + _i * 8192), 16, 0, 0); } while (0)
; #define PG8_LDA(dst, b, h) do { _Pragma("unroll") for (int m = 0; m < 4; ++m) _Pragma("unroll") for (int k = 0; k < 2; ++k) dst[m][k] = *(const PG8_LAS bf16x8*)(lds + PG8_SA(b, h) + aoff + m * 2048 + k * 1024); } while (0)
; #define PG8_LDB(dst, b, h) do { _Pragma("unroll") for (int n = 0; n < 2; ++n) _Pragma("unroll") for (int k = 0; k < 2; ++k) dst[n][k] = *(const PG8_LAS bf16x8*)(lds + PG8_SB(b, h) + boff + n * 2048 + k * 1024); } while (0)
; #define PG8_MMA(ai, bj, At, Bt) do { __builtin_amdgcn_s_setprio(1); _Pragma("unroll") for (int m = 0; m < 4; ++m) _Pragma("unroll") for (int n = 0; n < 2; ++n) _Pragma("unroll") for (int k = 0; k < 2; ++k) \
;         acc[ai][bj][m][n] = __builtin_amdgcn_mfma_f32_16x16x32_bf16(Bt[n][k], At[m][k], acc[ai][bj][m][n], 0, 0, 0); __builtin_amdgcn_s_setprio(0); } while (0)
; #define PG8_WAIT_V(n) asm volatile("s_waitcnt vmcnt(" #n ")" ::: "memory")
; #define PG8_WAIT_L(n) asm volatile("s_waitcnt lgkmcnt(" #n ")" ::: "memory")
; #define PG8_BAR __builtin_amdgcn_s_barrier()
; #define PG8_SCHED __builtin_amdgcn_sched_barrier(0)
; template <class Epi, class Sched, bool ALIGN_EPI = false, bool SP2 = false>
; __device__ __forceinline__ void gemm_phase(PG8_LAS unsigned char* lds, const Gemm g, const Sched& S, const Epi& E) {
;     ...
;             PG8_LDB(B0, 0, 0); PG8_LDB(B1, 0, 1); PG8_SCHED; PG8_LDA(At, 0, 0); PG8_STAGE(PG8_SA(1, 1), a1 + hstep, voffA);
;             PG8_WAIT_V(8); PG8_WAIT_L(0); PG8_BAR; PG8_MMA(0, 0, At, B0); PG8_MMA(0, 1, At, B1); PG8_BAR; PG8_SCHED;
;             PG8_LDA(At, 0, 1); PG8_STAGE(PG8_SB(0, 0), b2, voffB); PG8_STAGE(PG8_SB(0, 1), b2 + hstep, voffB); PG8_STAGE(PG8_SA(0, 0), a2, voffA);
;             PG8_WAIT_V(8); PG8_WAIT_L(0); PG8_BAR; PG8_MMA(1, 0, At, B0); PG8_MMA(1, 1, At, B1); PG8_BAR; PG8_SCHED;
.LBB0_2136:
	ds_read_b128 v[152:155], v149
	ds_read_b128 v[156:159], v149 offset:1024
	ds_read_b128 v[160:163], v149 offset:2048
	ds_read_b128 v[164:167], v149 offset:3072
	ds_read_b128 v[168:171], v150
	ds_read_b128 v[172:175], v150 offset:1024
	ds_read_b128 v[176:179], v150 offset:2048
	ds_read_b128 v[180:183], v150 offset:3072
	s_add_u32 s30, s28, 0xfff00080
	s_addc_u32 s31, s29, -1
	s_cmp_eq_u32 s68, 60
	s_cselect_b32 s35, s21, s31
	s_cselect_b32 s34, s64, s30
	s_cselect_b32 s31, s19, s67
	s_cselect_b32 s30, s65, s66
	v_lshl_add_u64 v[144:145], s[28:29], 0, v[136:137]
	s_add_i32 m0, s27, 0xc000
	ds_read_b128 v[184:187], v151
	ds_read_b128 v[188:191], v151 offset:1024
	ds_read_b128 v[192:195], v151 offset:2048
	ds_read_b128 v[196:199], v151 offset:3072
	ds_read_b128 v[200:203], v151 offset:4096
	ds_read_b128 v[204:207], v151 offset:5120
	ds_read_b128 v[208:211], v151 offset:6144
	ds_read_b128 v[212:215], v151 offset:7168
	global_load_lds_dwordx4 v[144:145], off
	v_lshl_add_u64 v[144:145], s[28:29], 0, v[138:139]
	s_add_i32 m0, s27, 0xe000
	s_nop 0
	global_load_lds_dwordx4 v[144:145], off
	s_waitcnt vmcnt(8)
	s_waitcnt lgkmcnt(0)
	s_barrier
	s_setprio 1
	s_waitcnt lgkmcnt(0)
	v_mfma_f32_16x16x32_bf16 v[124:127], v[152:155], v[184:187], v[124:127]
	v_mfma_f32_16x16x32_bf16 v[120:123], v[160:163], v[184:187], v[120:123]
	v_mfma_f32_16x16x32_bf16 v[108:111], v[152:155], v[192:195], v[108:111]
	v_mfma_f32_16x16x32_bf16 v[104:107], v[160:163], v[192:195], v[104:107]
	v_mfma_f32_16x16x32_bf16 v[92:95], v[152:155], v[200:203], v[92:95]
	v_mfma_f32_16x16x32_bf16 v[88:91], v[160:163], v[200:203], v[88:91]
	v_mfma_f32_16x16x32_bf16 v[76:79], v[152:155], v[208:211], v[76:79]
	v_mfma_f32_16x16x32_bf16 v[72:75], v[160:163], v[208:211], v[72:75]
	v_mfma_f32_16x16x32_bf16 v[124:127], v[156:159], v[188:191], v[124:127]
	v_mfma_f32_16x16x32_bf16 v[120:123], v[164:167], v[188:191], v[120:123]
	v_mfma_f32_16x16x32_bf16 v[108:111], v[156:159], v[196:199], v[108:111]
	v_mfma_f32_16x16x32_bf16 v[104:107], v[164:167], v[196:199], v[104:107]
	v_mfma_f32_16x16x32_bf16 v[92:95], v[156:159], v[204:207], v[92:95]
	v_mfma_f32_16x16x32_bf16 v[88:91], v[164:167], v[204:207], v[88:91]
	v_mfma_f32_16x16x32_bf16 v[76:79], v[156:159], v[212:215], v[76:79]
	v_mfma_f32_16x16x32_bf16 v[72:75], v[164:167], v[212:215], v[72:75]
	s_setprio 0
	s_setprio 1
	v_mfma_f32_16x16x32_bf16 v[116:119], v[168:171], v[184:187], v[116:119]
	v_mfma_f32_16x16x32_bf16 v[112:115], v[176:179], v[184:187], v[112:115]
	v_mfma_f32_16x16x32_bf16 v[100:103], v[168:171], v[192:195], v[100:103]
	v_mfma_f32_16x16x32_bf16 v[96:99], v[176:179], v[192:195], v[96:99]
	v_mfma_f32_16x16x32_bf16 v[84:87], v[168:171], v[200:203], v[84:87]
	v_mfma_f32_16x16x32_bf16 v[80:83], v[176:179], v[200:203], v[80:83]
	v_mfma_f32_16x16x32_bf16 v[68:71], v[168:171], v[208:211], v[68:71]
	v_mfma_f32_16x16x32_bf16 v[64:67], v[176:179], v[208:211], v[64:67]
	v_mfma_f32_16x16x32_bf16 v[116:119], v[172:175], v[188:191], v[116:119]
	v_mfma_f32_16x16x32_bf16 v[112:115], v[180:183], v[188:191], v[112:115]
	v_mfma_f32_16x16x32_bf16 v[100:103], v[172:175], v[196:199], v[100:103]
	v_mfma_f32_16x16x32_bf16 v[96:99], v[180:183], v[196:199], v[96:99]
	v_mfma_f32_16x16x32_bf16 v[84:87], v[172:175], v[204:207], v[84:87]
	v_mfma_f32_16x16x32_bf16 v[80:83], v[180:183], v[204:207], v[80:83]
	v_mfma_f32_16x16x32_bf16 v[68:71], v[172:175], v[212:215], v[68:71]
	v_mfma_f32_16x16x32_bf16 v[64:67], v[180:183], v[212:215], v[64:67]
	s_setprio 0
	s_barrier
	s_add_i32 s69, s51, s39
	v_lshl_add_u64 v[144:145], s[30:31], 0, v[132:133]
	s_mov_b32 m0, s69
	ds_read_b128 v[184:187], v151 offset:16384
	ds_read_b128 v[188:191], v151 offset:17408
	ds_read_b128 v[192:195], v151 offset:18432
	ds_read_b128 v[196:199], v151 offset:19456
	ds_read_b128 v[200:203], v151 offset:20480
	ds_read_b128 v[204:207], v151 offset:21504
	ds_read_b128 v[208:211], v151 offset:22528
	ds_read_b128 v[212:215], v151 offset:23552
	global_load_lds_dwordx4 v[144:145], off
	s_add_i32 m0, s69, 0x2000
	s_add_u32 s70, s30, 0x100000
	v_lshl_add_u64 v[216:217], s[30:31], 0, v[128:129]
	s_addc_u32 s71, s31, 0
	s_add_i32 s69, s52, s39
	global_load_lds_dwordx4 v[216:217], off
	v_lshl_add_u64 v[218:219], s[70:71], 0, v[132:133]
	s_mov_b32 m0, s69
	v_lshl_add_u64 v[220:221], s[34:35], 0, v[130:131]
	global_load_lds_dwordx4 v[218:219], off
	v_lshl_add_u64 v[218:219], s[70:71], 0, v[128:129]
	s_add_i32 m0, s69, 0x2000
	s_nop 0
	global_load_lds_dwordx4 v[218:219], off
	v_lshl_add_u64 v[218:219], s[34:35], 0, v[134:135]
	s_mov_b32 m0, s27
	s_nop 0
	global_load_lds_dwordx4 v[218:219], off
	s_mov_b32 m0, s42
	s_nop 0
	global_load_lds_dwordx4 v[220:221], off
	s_waitcnt vmcnt(8)
	s_waitcnt lgkmcnt(0)
	s_barrier
; #define PG8_STAGE(bufoff, gbase, voff) do { _Pragma("unroll") for (int _i = 0; _i < 2; ++_i) \
;         __builtin_amdgcn_global_load_lds((const unsigned*)((const char*)(gbase) + (voff)[_i]), (PG8_LAS unsigned*)(lds + (bufoff) + ldsw + _i * 8192), 16, 0, 0); } while (0)
; #define PG8_LDA(dst, b, h) do { _Pragma("unroll") for (int m = 0; m < 4; ++m) _Pragma("unroll") for (int k = 0; k < 2; ++k) dst[m][k] = *(const PG8_LAS bf16x8*)(lds + PG8_SA(b, h) + aoff + m * 2048 + k * 1024); } while (0)
; #define PG8_LDB(dst, b, h) do { _Pragma("unroll") for (int n = 0; n < 2; ++n) _Pragma("unroll") for (int k = 0; k < 2; ++k) dst[n][k] = *(const PG8_LAS bf16x8*)(lds + PG8_SB(b, h) + boff + n * 2048 + k * 1024); } while (0)
; #define PG8_MMA(ai, bj, At, Bt) do { __builtin_amdgcn_s_setprio(1); _Pragma("unroll") for (int m = 0; m < 4; ++m) _Pragma("unroll") for (int n = 0; n < 2; ++n) _Pragma("unroll") for (int k = 0; k < 2; ++k) \
;         acc[ai][bj][m][n] = __builtin_amdgcn_mfma_f32_16x16x32_bf16(Bt[n][k], At[m][k], acc[ai][bj][m][n], 0, 0, 0); __builtin_amdgcn_s_setprio(0); } while (0)
; #define PG8_WAIT_V(n) asm volatile("s_waitcnt vmcnt(" #n ")" ::: "memory")
; #define PG8_WAIT_L(n) asm volatile("s_waitcnt lgkmcnt(" #n ")" ::: "memory")
; #define PG8_BAR __builtin_amdgcn_s_barrier()
; #define PG8_SCHED __builtin_amdgcn_sched_barrier(0)
; template <class Epi, class Sched, bool ALIGN_EPI = false, bool SP2 = false>
; __device__ __forceinline__ void gemm_phase(PG8_LAS unsigned char* lds, const Gemm g, const Sched& S, const Epi& E) {
;     ...
;             PG8_WAIT_V(8); PG8_WAIT_L(0); PG8_BAR; PG8_MMA(1, 0, At, B0); PG8_MMA(1, 1, At, B1); PG8_BAR; PG8_SCHED;
;             PG8_LDB(B0, 1, 0); PG8_LDB(B1, 1, 1); PG8_SCHED; PG8_LDA(At, 1, 0); PG8_STAGE(PG8_SA(0, 1), a2 + hstep, voffA);
;             PG8_WAIT_V(8); PG8_WAIT_L(0); PG8_BAR; PG8_MMA(0, 0, At, B0); PG8_MMA(0, 1, At, B1); PG8_BAR; PG8_SCHED;
	s_setprio 1
	s_waitcnt lgkmcnt(0)
	v_mfma_f32_16x16x32_bf16 v[60:63], v[152:155], v[184:187], v[60:63]
	v_mfma_f32_16x16x32_bf16 v[56:59], v[160:163], v[184:187], v[56:59]
	v_mfma_f32_16x16x32_bf16 v[44:47], v[152:155], v[192:195], v[44:47]
	v_mfma_f32_16x16x32_bf16 v[40:43], v[160:163], v[192:195], v[40:43]
	v_mfma_f32_16x16x32_bf16 v[28:31], v[152:155], v[200:203], v[28:31]
	v_mfma_f32_16x16x32_bf16 v[24:27], v[160:163], v[200:203], v[24:27]
	v_mfma_f32_16x16x32_bf16 v[12:15], v[152:155], v[208:211], v[12:15]
	v_mfma_f32_16x16x32_bf16 v[8:11], v[160:163], v[208:211], v[8:11]
	v_mfma_f32_16x16x32_bf16 v[60:63], v[156:159], v[188:191], v[60:63]
	v_mfma_f32_16x16x32_bf16 v[56:59], v[164:167], v[188:191], v[56:59]
	v_mfma_f32_16x16x32_bf16 v[44:47], v[156:159], v[196:199], v[44:47]
	v_mfma_f32_16x16x32_bf16 v[40:43], v[164:167], v[196:199], v[40:43]
	v_mfma_f32_16x16x32_bf16 v[28:31], v[156:159], v[204:207], v[28:31]
	v_mfma_f32_16x16x32_bf16 v[24:27], v[164:167], v[204:207], v[24:27]
	v_mfma_f32_16x16x32_bf16 v[12:15], v[156:159], v[212:215], v[12:15]
	v_mfma_f32_16x16x32_bf16 v[8:11], v[164:167], v[212:215], v[8:11]
	s_setprio 0
	s_setprio 1
	v_mfma_f32_16x16x32_bf16 v[52:55], v[168:171], v[184:187], v[52:55]
	v_mfma_f32_16x16x32_bf16 v[48:51], v[176:179], v[184:187], v[48:51]
	v_mfma_f32_16x16x32_bf16 v[36:39], v[168:171], v[192:195], v[36:39]
	v_mfma_f32_16x16x32_bf16 v[32:35], v[176:179], v[192:195], v[32:35]
	v_mfma_f32_16x16x32_bf16 v[20:23], v[168:171], v[200:203], v[20:23]
	v_mfma_f32_16x16x32_bf16 v[16:19], v[176:179], v[200:203], v[16:19]
	v_mfma_f32_16x16x32_bf16 v[4:7], v[168:171], v[208:211], v[4:7]
	v_mfma_f32_16x16x32_bf16 v[0:3], v[176:179], v[208:211], v[0:3]
	v_mfma_f32_16x16x32_bf16 v[52:55], v[172:175], v[188:191], v[52:55]
	v_mfma_f32_16x16x32_bf16 v[48:51], v[180:183], v[188:191], v[48:51]
	v_mfma_f32_16x16x32_bf16 v[36:39], v[172:175], v[196:199], v[36:39]
	v_mfma_f32_16x16x32_bf16 v[32:35], v[180:183], v[196:199], v[32:35]
	v_mfma_f32_16x16x32_bf16 v[20:23], v[172:175], v[204:207], v[20:23]
	v_mfma_f32_16x16x32_bf16 v[16:19], v[180:183], v[204:207], v[16:19]
	v_mfma_f32_16x16x32_bf16 v[4:7], v[172:175], v[212:215], v[4:7]
	v_mfma_f32_16x16x32_bf16 v[0:3], v[180:183], v[212:215], v[0:3]
	s_setprio 0
	s_barrier
	s_add_i32 s69, 0, 0x18000
	s_add_i32 s70, 0, 0x1c000
	v_add_u32_e32 v164, s69, v147
	v_add_u32_e32 v180, s70, v147
	ds_read_b128 v[152:155], v164
	ds_read_b128 v[156:159], v164 offset:1024
	ds_read_b128 v[160:163], v164 offset:2048
	ds_read_b128 v[164:167], v164 offset:3072
	ds_read_b128 v[168:171], v180
	ds_read_b128 v[172:175], v180 offset:1024
	ds_read_b128 v[176:179], v180 offset:2048
	ds_read_b128 v[180:183], v180 offset:3072
	s_add_u32 s34, s34, 0x100000
	s_addc_u32 s35, s35, 0
	s_mov_b32 m0, s43
	v_lshl_add_u64 v[222:223], s[34:35], 0, v[134:135]
	ds_read_b128 v[184:187], v151 offset:32768
	ds_read_b128 v[188:191], v151 offset:33792
	ds_read_b128 v[192:195], v151 offset:34816
	ds_read_b128 v[196:199], v151 offset:35840
	ds_read_b128 v[200:203], v151 offset:36864
	ds_read_b128 v[204:207], v151 offset:37888
	ds_read_b128 v[208:211], v151 offset:38912
	ds_read_b128 v[212:215], v151 offset:39936
	global_load_lds_dwordx4 v[222:223], off
	v_lshl_add_u64 v[222:223], s[34:35], 0, v[130:131]
	s_mov_b32 m0, s46
	s_nop 0
	global_load_lds_dwordx4 v[222:223], off
	s_waitcnt vmcnt(8)
	s_waitcnt lgkmcnt(0)
	s_barrier
	s_setprio 1
	s_waitcnt lgkmcnt(0)
	v_mfma_f32_16x16x32_bf16 v[124:127], v[152:155], v[184:187], v[124:127]
	v_mfma_f32_16x16x32_bf16 v[120:123], v[160:163], v[184:187], v[120:123]
	v_mfma_f32_16x16x32_bf16 v[108:111], v[152:155], v[192:195], v[108:111]
	v_mfma_f32_16x16x32_bf16 v[104:107], v[160:163], v[192:195], v[104:107]
	v_mfma_f32_16x16x32_bf16 v[92:95], v[152:155], v[200:203], v[92:95]
	v_mfma_f32_16x16x32_bf16 v[88:91], v[160:163], v[200:203], v[88:91]
	v_mfma_f32_16x16x32_bf16 v[76:79], v[152:155], v[208:211], v[76:79]
	v_mfma_f32_16x16x32_bf16 v[72:75], v[160:163], v[208:211], v[72:75]
	v_mfma_f32_16x16x32_bf16 v[124:127], v[156:159], v[188:191], v[124:127]
	v_mfma_f32_16x16x32_bf16 v[120:123], v[164:167], v[188:191], v[120:123]
	v_mfma_f32_16x16x32_bf16 v[108:111], v[156:159], v[196:199], v[108:111]
	v_mfma_f32_16x16x32_bf16 v[104:107], v[164:167], v[196:199], v[104:107]
	v_mfma_f32_16x16x32_bf16 v[92:95], v[156:159], v[204:207], v[92:95]
	v_mfma_f32_16x16x32_bf16 v[88:91], v[164:167], v[204:207], v[88:91]
	v_mfma_f32_16x16x32_bf16 v[76:79], v[156:159], v[212:215], v[76:79]
	v_mfma_f32_16x16x32_bf16 v[72:75], v[164:167], v[212:215], v[72:75]
	s_setprio 0
	s_setprio 1
	v_mfma_f32_16x16x32_bf16 v[116:119], v[168:171], v[184:187], v[116:119]
	v_mfma_f32_16x16x32_bf16 v[112:115], v[176:179], v[184:187], v[112:115]
	v_mfma_f32_16x16x32_bf16 v[100:103], v[168:171], v[192:195], v[100:103]
	v_mfma_f32_16x16x32_bf16 v[96:99], v[176:179], v[192:195], v[96:99]
	v_mfma_f32_16x16x32_bf16 v[84:87], v[168:171], v[200:203], v[84:87]
	v_mfma_f32_16x16x32_bf16 v[80:83], v[176:179], v[200:203], v[80:83]
	v_mfma_f32_16x16x32_bf16 v[68:71], v[168:171], v[208:211], v[68:71]
	v_mfma_f32_16x16x32_bf16 v[64:67], v[176:179], v[208:211], v[64:67]
	v_mfma_f32_16x16x32_bf16 v[116:119], v[172:175], v[188:191], v[116:119]
	v_mfma_f32_16x16x32_bf16 v[112:115], v[180:183], v[188:191], v[112:115]
	v_mfma_f32_16x16x32_bf16 v[100:103], v[172:175], v[196:199], v[100:103]
	v_mfma_f32_16x16x32_bf16 v[96:99], v[180:183], v[196:199], v[96:99]
	v_mfma_f32_16x16x32_bf16 v[84:87], v[172:175], v[204:207], v[84:87]
	v_mfma_f32_16x16x32_bf16 v[80:83], v[180:183], v[204:207], v[80:83]
	v_mfma_f32_16x16x32_bf16 v[68:71], v[172:175], v[212:215], v[68:71]
	v_mfma_f32_16x16x32_bf16 v[64:67], v[180:183], v[212:215], v[64:67]
	s_setprio 0
	s_barrier
; #define PG8_STAGE(bufoff, gbase, voff) do { _Pragma("unroll") for (int _i = 0; _i < 2; ++_i) \
;         __builtin_amdgcn_global_load_lds((const unsigned*)((const char*)(gbase) + (voff)[_i]), (PG8_LAS unsigned*)(lds + (bufoff) + ldsw + _i * 8192), 16, 0, 0); } while (0)
; #define PG8_LDA(dst, b, h) do { _Pragma("unroll") for (int m = 0; m < 4; ++m) _Pragma("unroll") for (int k = 0; k < 2; ++k) dst[m][k] = *(const PG8_LAS bf16x8*)(lds + PG8_SA(b, h) + aoff + m * 2048 + k * 1024); } while (0)
; #define PG8_MMA(ai, bj, At, Bt) do { __builtin_amdgcn_s_setprio(1); _Pragma("unroll") for (int m = 0; m < 4; ++m) _Pragma("unroll") for (int n = 0; n < 2; ++n) _Pragma("unroll") for (int k = 0; k < 2; ++k) \
;         acc[ai][bj][m][n] = __builtin_amdgcn_mfma_f32_16x16x32_bf16(Bt[n][k], At[m][k], acc[ai][bj][m][n], 0, 0, 0); __builtin_amdgcn_s_setprio(0); } while (0)
; #define PG8_WAIT_V(n) asm volatile("s_waitcnt vmcnt(" #n ")" ::: "memory")
; #define PG8_WAIT_L(n) asm volatile("s_waitcnt lgkmcnt(" #n ")" ::: "memory")
; #define PG8_BAR __builtin_amdgcn_s_barrier()
; #define PG8_SCHED __builtin_amdgcn_sched_barrier(0)
; template <class Epi, class Sched, bool ALIGN_EPI = false, bool SP2 = false>
; __device__ __forceinline__ void gemm_phase(PG8_LAS unsigned char* lds, const Gemm g, const Sched& S, const Epi& E) {
;     ...
;             PG8_LDA(At, 1, 1); PG8_STAGE(PG8_SB(1, 0), b3, voffB); PG8_STAGE(PG8_SB(1, 1), b3 + hstep, voffB); PG8_STAGE(PG8_SA(1, 0), a3, voffA);
;             PG8_WAIT_V(8); PG8_WAIT_L(0); PG8_BAR; PG8_MMA(1, 0, At, B0); PG8_MMA(1, 1, At, B1); PG8_BAR; PG8_SCHED;
;     __device__ __forceinline__ void operator()(const f32x4 (&acc)[2][2][4][2], const Unit& u, int wr, int wc, int fr, int fq) const {
;         const int rbase = u.pm * 256 + wr * 64 + fr, cb = u.pn * 256 + wc * 32 + fq * 8;
; #pragma unroll
;         for (int ai = 0; ai < 2; ++ai)
; #pragma unroll
;             for (int m = 0; m < 4; ++m) { float* yr = y + (size_t)(rbase + ai * 128 + m * 16) * 1024 + cb;
; #pragma unroll
;                 for (int bj = 0; bj < 2; ++bj) { float* yp = yr + bj * 128; const f32x4 a = *(const f32x4*)yp + acc[ai][bj][m][0], b = *(const f32x4*)(yp + 4) + acc[ai][bj][m][1]; *(f32x4*)yp = a; *(f32x4*)(yp + 4) = b; }
	s_add_i32 s34, s69, s39
	v_lshl_add_u64 v[144:145], v[144:145], 0, s[6:7]
	s_mov_b32 m0, s34
	ds_read_b128 v[184:187], v151 offset:49152
	ds_read_b128 v[188:191], v151 offset:50176
	ds_read_b128 v[192:195], v151 offset:51200
	ds_read_b128 v[196:199], v151 offset:52224
	ds_read_b128 v[200:203], v151 offset:53248
	ds_read_b128 v[204:207], v151 offset:54272
	ds_read_b128 v[208:211], v151 offset:55296
	ds_read_b128 v[212:215], v151 offset:56320
	global_load_lds_dwordx4 v[144:145], off
	s_add_i32 m0, s34, 0x2000
	s_add_u32 s30, s30, 0x100080
	v_lshl_add_u64 v[144:145], v[216:217], 0, s[6:7]
	s_addc_u32 s31, s31, 0
	s_add_i32 s34, s70, s39
	global_load_lds_dwordx4 v[144:145], off
	v_lshl_add_u64 v[144:145], s[30:31], 0, v[132:133]
	s_mov_b32 m0, s34
	s_nop 0
	global_load_lds_dwordx4 v[144:145], off
	v_lshl_add_u64 v[144:145], s[30:31], 0, v[128:129]
	s_add_i32 m0, s34, 0x2000
	s_nop 0
	global_load_lds_dwordx4 v[144:145], off
	v_lshl_add_u64 v[144:145], v[218:219], 0, s[6:7]
	s_mov_b32 m0, s48
	s_nop 0
	global_load_lds_dwordx4 v[144:145], off
	v_lshl_add_u64 v[144:145], v[220:221], 0, s[6:7]
	s_mov_b32 m0, s49
	s_nop 0
	global_load_lds_dwordx4 v[144:145], off
	s_waitcnt vmcnt(8)
	s_waitcnt lgkmcnt(0)
	s_barrier
	s_setprio 1
	s_waitcnt lgkmcnt(0)
	v_mfma_f32_16x16x32_bf16 v[60:63], v[152:155], v[184:187], v[60:63]
	v_mfma_f32_16x16x32_bf16 v[56:59], v[160:163], v[184:187], v[56:59]
	v_mfma_f32_16x16x32_bf16 v[44:47], v[152:155], v[192:195], v[44:47]
	v_mfma_f32_16x16x32_bf16 v[40:43], v[160:163], v[192:195], v[40:43]
	v_mfma_f32_16x16x32_bf16 v[28:31], v[152:155], v[200:203], v[28:31]
	v_mfma_f32_16x16x32_bf16 v[24:27], v[160:163], v[200:203], v[24:27]
	v_mfma_f32_16x16x32_bf16 v[12:15], v[152:155], v[208:211], v[12:15]
	v_mfma_f32_16x16x32_bf16 v[8:11], v[160:163], v[208:211], v[8:11]
	v_mfma_f32_16x16x32_bf16 v[60:63], v[156:159], v[188:191], v[60:63]
	v_mfma_f32_16x16x32_bf16 v[56:59], v[164:167], v[188:191], v[56:59]
	v_mfma_f32_16x16x32_bf16 v[44:47], v[156:159], v[196:199], v[44:47]
	v_mfma_f32_16x16x32_bf16 v[40:43], v[164:167], v[196:199], v[40:43]
	v_mfma_f32_16x16x32_bf16 v[28:31], v[156:159], v[204:207], v[28:31]
	v_mfma_f32_16x16x32_bf16 v[24:27], v[164:167], v[204:207], v[24:27]
	v_mfma_f32_16x16x32_bf16 v[12:15], v[156:159], v[212:215], v[12:15]
	v_mfma_f32_16x16x32_bf16 v[8:11], v[164:167], v[212:215], v[8:11]
	s_setprio 0
	s_setprio 1
	v_mfma_f32_16x16x32_bf16 v[52:55], v[168:171], v[184:187], v[52:55]
	v_mfma_f32_16x16x32_bf16 v[48:51], v[176:179], v[184:187], v[48:51]
	v_mfma_f32_16x16x32_bf16 v[36:39], v[168:171], v[192:195], v[36:39]
	v_mfma_f32_16x16x32_bf16 v[32:35], v[176:179], v[192:195], v[32:35]
	v_mfma_f32_16x16x32_bf16 v[20:23], v[168:171], v[200:203], v[20:23]
	v_mfma_f32_16x16x32_bf16 v[16:19], v[176:179], v[200:203], v[16:19]
	v_mfma_f32_16x16x32_bf16 v[4:7], v[168:171], v[208:211], v[4:7]
	v_mfma_f32_16x16x32_bf16 v[0:3], v[176:179], v[208:211], v[0:3]
	v_mfma_f32_16x16x32_bf16 v[52:55], v[172:175], v[188:191], v[52:55]
	v_mfma_f32_16x16x32_bf16 v[48:51], v[180:183], v[188:191], v[48:51]
	v_mfma_f32_16x16x32_bf16 v[36:39], v[172:175], v[196:199], v[36:39]
	v_mfma_f32_16x16x32_bf16 v[32:35], v[180:183], v[196:199], v[32:35]
	v_mfma_f32_16x16x32_bf16 v[20:23], v[172:175], v[204:207], v[20:23]
	v_mfma_f32_16x16x32_bf16 v[16:19], v[180:183], v[204:207], v[16:19]
	v_mfma_f32_16x16x32_bf16 v[4:7], v[172:175], v[212:215], v[4:7]
	v_mfma_f32_16x16x32_bf16 v[0:3], v[180:183], v[212:215], v[0:3]
	s_setprio 0
	s_barrier
	s_add_i32 s68, s68, 2
	s_add_u32 s28, s28, 0x100
	s_addc_u32 s29, s29, 0
	s_add_u32 s66, s66, 0x100
	s_addc_u32 s67, s67, 0
	s_cmp_gt_u32 s68, 61
	s_cbranch_scc0 .LBB0_2136
	v_and_b32_e32 v216, 0xfffffff7, v146
	v_lshl_add_u32 v216, s26, 8, v216
	v_bfe_u32 v220, v146, 3, 1
	v_lshl_add_u32 v220, v220, 2, v148
	v_lshl_or_b32 v220, s63, 8, v220
	v_ashrrev_i32_e32 v217, 31, v216
	v_ashrrev_i32_e32 v221, 31, v220
	v_lshlrev_b64 v[216:217], 12, v[216:217]
	v_lshlrev_b64 v[220:221], 2, v[220:221]
	v_lshl_add_u64 v[216:217], s[84:85], 0, v[216:217]
	v_lshl_add_u64 v[216:217], v[216:217], 0, v[220:221]
	s_mov_b64 s[98:99], 0x8000
	v_lshl_add_u64 v[218:219], v[216:217], 0, s[98:99]
	v_mov_b64_e32 v[220:221], v[216:217]
	v_mov_b64_e32 v[222:223], v[218:219]
	s_mov_b64 s[98:99], 0x10000
	s_mov_b64 s[100:101], 0x50000
	global_load_dwordx4 v[152:155], v[216:217], off
	global_load_dwordx4 v[156:159], v[218:219], off
	global_load_dwordx4 v[160:163], v[216:217], off offset:512
	global_load_dwordx4 v[164:167], v[218:219], off offset:512
	v_lshl_add_u64 v[216:217], v[216:217], 0, s[98:99]
	v_lshl_add_u64 v[218:219], v[218:219], 0, s[98:99]
	global_load_dwordx4 v[168:171], v[216:217], off
	global_load_dwordx4 v[172:175], v[218:219], off
	global_load_dwordx4 v[176:179], v[216:217], off offset:512
	global_load_dwordx4 v[180:183], v[218:219], off offset:512
	v_lshl_add_u64 v[216:217], v[216:217], 0, s[98:99]
	v_lshl_add_u64 v[218:219], v[218:219], 0, s[98:99]
	global_load_dwordx4 v[184:187], v[216:217], off
	global_load_dwordx4 v[188:191], v[218:219], off
	global_load_dwordx4 v[192:195], v[216:217], off offset:512
	global_load_dwordx4 v[196:199], v[218:219], off offset:512
	v_lshl_add_u64 v[216:217], v[216:217], 0, s[98:99]
	v_lshl_add_u64 v[218:219], v[218:219], 0, s[98:99]
	global_load_dwordx4 v[200:203], v[216:217], off
	global_load_dwordx4 v[204:207], v[218:219], off
	global_load_dwordx4 v[208:211], v[216:217], off offset:512
	global_load_dwordx4 v[212:215], v[218:219], off offset:512
	v_lshl_add_u64 v[216:217], v[216:217], 0, s[100:101]
	v_lshl_add_u64 v[218:219], v[218:219], 0, s[100:101]
	global_load_dwordx4 v[228:231], v[216:217], off
	global_load_dwordx4 v[232:235], v[218:219], off
	global_load_dwordx4 v[236:239], v[216:217], off offset:512
	global_load_dwordx4 v[240:243], v[218:219], off offset:512
	v_lshl_add_u64 v[216:217], v[216:217], 0, s[98:99]
	v_lshl_add_u64 v[218:219], v[218:219], 0, s[98:99]
	s_and_b64 vcc, exec, s[8:9]
	s_cbranch_vccz .LBB0_2139
	s_barrier
;     __device__ __forceinline__ void operator()(const f32x4 (&acc)[2][2][4][2], const Unit& u, int wr, int wc, int fr, int fq) const {
;         const int rbase = u.pm * 256 + wr * 64 + fr, cb = u.pn * 256 + wc * 32 + fq * 8;
; #pragma unroll
;         for (int ai = 0; ai < 2; ++ai)
; #pragma unroll
;             for (int m = 0; m < 4; ++m) { float* yr = y + (size_t)(rbase + ai * 128 + m * 16) * 1024 + cb;
; #pragma unroll
;                 for (int bj = 0; bj < 2; ++bj) { float* yp = yr + bj * 128; const f32x4 a = *(const f32x4*)yp + acc[ai][bj][m][0], b = *(const f32x4*)(yp + 4) + acc[ai][bj][m][1]; *(f32x4*)yp = a; *(f32x4*)(yp + 4) = b; }
;                 asm volatile("" ::: "memory"); }
.LBB0_2139:
	v_and_b32_e32 v244, 8, v146
	v_cmp_eq_u32_e32 vcc, 0, v244
	s_nop 1
	v_mov_b32_dpp v244, v124 row_ror:8 row_mask:0xf bank_mask:0xf
	v_mov_b32_dpp v245, v125 row_ror:8 row_mask:0xf bank_mask:0xf
	v_mov_b32_dpp v246, v126 row_ror:8 row_mask:0xf bank_mask:0xf
	v_mov_b32_dpp v247, v127 row_ror:8 row_mask:0xf bank_mask:0xf
	v_mov_b32_dpp v248, v120 row_ror:8 row_mask:0xf bank_mask:0xf
	v_mov_b32_dpp v249, v121 row_ror:8 row_mask:0xf bank_mask:0xf
	v_mov_b32_dpp v250, v122 row_ror:8 row_mask:0xf bank_mask:0xf
	v_mov_b32_dpp v251, v123 row_ror:8 row_mask:0xf bank_mask:0xf
	s_nop 0
	v_cndmask_b32_e32 v124, v248, v124, vcc
	v_cndmask_b32_e32 v125, v249, v125, vcc
	v_cndmask_b32_e32 v126, v250, v126, vcc
	v_cndmask_b32_e32 v127, v251, v127, vcc
	v_cndmask_b32_e32 v120, v120, v244, vcc
	v_cndmask_b32_e32 v121, v121, v245, vcc
	v_cndmask_b32_e32 v122, v122, v246, vcc
	v_cndmask_b32_e32 v123, v123, v247, vcc
	v_mov_b32_dpp v244, v116 row_ror:8 row_mask:0xf bank_mask:0xf
	v_mov_b32_dpp v245, v117 row_ror:8 row_mask:0xf bank_mask:0xf
	v_mov_b32_dpp v246, v118 row_ror:8 row_mask:0xf bank_mask:0xf
	v_mov_b32_dpp v247, v119 row_ror:8 row_mask:0xf bank_mask:0xf
	v_mov_b32_dpp v248, v112 row_ror:8 row_mask:0xf bank_mask:0xf
	v_mov_b32_dpp v249, v113 row_ror:8 row_mask:0xf bank_mask:0xf
	v_mov_b32_dpp v250, v114 row_ror:8 row_mask:0xf bank_mask:0xf
	v_mov_b32_dpp v251, v115 row_ror:8 row_mask:0xf bank_mask:0xf
	s_nop 0
	v_cndmask_b32_e32 v116, v248, v116, vcc
	v_cndmask_b32_e32 v117, v249, v117, vcc
	v_cndmask_b32_e32 v118, v250, v118, vcc
	v_cndmask_b32_e32 v119, v251, v119, vcc
	v_cndmask_b32_e32 v112, v112, v244, vcc
	v_cndmask_b32_e32 v113, v113, v245, vcc
	v_cndmask_b32_e32 v114, v114, v246, vcc
	v_cndmask_b32_e32 v115, v115, v247, vcc
	s_waitcnt vmcnt(16)
	v_pk_add_f32 v[124:125], v[124:125], v[152:153]
	v_pk_add_f32 v[126:127], v[126:127], v[154:155]
	v_pk_add_f32 v[120:121], v[120:121], v[156:157]
	v_pk_add_f32 v[122:123], v[122:123], v[158:159]
	v_pk_add_f32 v[116:117], v[116:117], v[160:161]
	v_pk_add_f32 v[118:119], v[118:119], v[162:163]
	v_pk_add_f32 v[112:113], v[112:113], v[164:165]
	v_pk_add_f32 v[114:115], v[114:115], v[166:167]
	global_store_dwordx4 v[220:221], v[124:127], off
	global_store_dwordx4 v[222:223], v[120:123], off
	global_store_dwordx4 v[220:221], v[116:119], off offset:512
	global_store_dwordx4 v[222:223], v[112:115], off offset:512
	v_lshl_add_u64 v[220:221], v[220:221], 0, s[98:99]
	v_lshl_add_u64 v[222:223], v[222:223], 0, s[98:99]
	global_load_dwordx4 v[152:155], v[216:217], off
	global_load_dwordx4 v[156:159], v[218:219], off
	global_load_dwordx4 v[160:163], v[216:217], off offset:512
	global_load_dwordx4 v[164:167], v[218:219], off offset:512
	v_lshl_add_u64 v[216:217], v[216:217], 0, s[98:99]
	v_lshl_add_u64 v[218:219], v[218:219], 0, s[98:99]
	v_mov_b32_dpp v244, v108 row_ror:8 row_mask:0xf bank_mask:0xf
	v_mov_b32_dpp v245, v109 row_ror:8 row_mask:0xf bank_mask:0xf
	v_mov_b32_dpp v246, v110 row_ror:8 row_mask:0xf bank_mask:0xf
	v_mov_b32_dpp v247, v111 row_ror:8 row_mask:0xf bank_mask:0xf
	v_mov_b32_dpp v248, v104 row_ror:8 row_mask:0xf bank_mask:0xf
	v_mov_b32_dpp v249, v105 row_ror:8 row_mask:0xf bank_mask:0xf
	v_mov_b32_dpp v250, v106 row_ror:8 row_mask:0xf bank_mask:0xf
	v_mov_b32_dpp v251, v107 row_ror:8 row_mask:0xf bank_mask:0xf
	s_nop 0
	v_cndmask_b32_e32 v108, v248, v108, vcc
	v_cndmask_b32_e32 v109, v249, v109, vcc
	v_cndmask_b32_e32 v110, v250, v110, vcc
	v_cndmask_b32_e32 v111, v251, v111, vcc
	v_cndmask_b32_e32 v104, v104, v244, vcc
	v_cndmask_b32_e32 v105, v105, v245, vcc
	v_cndmask_b32_e32 v106, v106, v246, vcc
	v_cndmask_b32_e32 v107, v107, v247, vcc
	v_mov_b32_dpp v244, v100 row_ror:8 row_mask:0xf bank_mask:0xf
	v_mov_b32_dpp v245, v101 row_ror:8 row_mask:0xf bank_mask:0xf
	v_mov_b32_dpp v246, v102 row_ror:8 row_mask:0xf bank_mask:0xf
	v_mov_b32_dpp v247, v103 row_ror:8 row_mask:0xf bank_mask:0xf
	v_mov_b32_dpp v248, v96 row_ror:8 row_mask:0xf bank_mask:0xf
	v_mov_b32_dpp v249, v97 row_ror:8 row_mask:0xf bank_mask:0xf
	v_mov_b32_dpp v250, v98 row_ror:8 row_mask:0xf bank_mask:0xf
	v_mov_b32_dpp v251, v99 row_ror:8 row_mask:0xf bank_mask:0xf
	s_nop 0
	v_cndmask_b32_e32 v100, v248, v100, vcc
	v_cndmask_b32_e32 v101, v249, v101, vcc
	v_cndmask_b32_e32 v102, v250, v102, vcc
	v_cndmask_b32_e32 v103, v251, v103, vcc
	v_cndmask_b32_e32 v96, v96, v244, vcc
	v_cndmask_b32_e32 v97, v97, v245, vcc
	v_cndmask_b32_e32 v98, v98, v246, vcc
	v_cndmask_b32_e32 v99, v99, v247, vcc
	s_waitcnt vmcnt(20)
;     __device__ __forceinline__ void operator()(const f32x4 (&acc)[2][2][4][2], const Unit& u, int wr, int wc, int fr, int fq) const {
;         const int rbase = u.pm * 256 + wr * 64 + fr, cb = u.pn * 256 + wc * 32 + fq * 8;
; #pragma unroll
;         for (int ai = 0; ai < 2; ++ai)
; #pragma unroll
;             for (int m = 0; m < 4; ++m) { float* yr = y + (size_t)(rbase + ai * 128 + m * 16) * 1024 + cb;
; #pragma unroll
;                 for (int bj = 0; bj < 2; ++bj) { float* yp = yr + bj * 128; const f32x4 a = *(const f32x4*)yp + acc[ai][bj][m][0], b = *(const f32x4*)(yp + 4) + acc[ai][bj][m][1]; *(f32x4*)yp = a; *(f32x4*)(yp + 4) = b; }
;                 asm volatile("" ::: "memory"); }
	v_pk_add_f32 v[108:109], v[108:109], v[168:169]
	v_pk_add_f32 v[110:111], v[110:111], v[170:171]
	v_pk_add_f32 v[104:105], v[104:105], v[172:173]
	v_pk_add_f32 v[106:107], v[106:107], v[174:175]
	v_pk_add_f32 v[100:101], v[100:101], v[176:177]
	v_pk_add_f32 v[102:103], v[102:103], v[178:179]
	v_pk_add_f32 v[96:97], v[96:97], v[180:181]
	v_pk_add_f32 v[98:99], v[98:99], v[182:183]
	global_store_dwordx4 v[220:221], v[108:111], off
	global_store_dwordx4 v[222:223], v[104:107], off
	global_store_dwordx4 v[220:221], v[100:103], off offset:512
	global_store_dwordx4 v[222:223], v[96:99], off offset:512
	v_lshl_add_u64 v[220:221], v[220:221], 0, s[98:99]
	v_lshl_add_u64 v[222:223], v[222:223], 0, s[98:99]
	global_load_dwordx4 v[168:171], v[216:217], off
	global_load_dwordx4 v[172:175], v[218:219], off
	global_load_dwordx4 v[176:179], v[216:217], off offset:512
	global_load_dwordx4 v[180:183], v[218:219], off offset:512
	v_lshl_add_u64 v[216:217], v[216:217], 0, s[98:99]
	v_lshl_add_u64 v[218:219], v[218:219], 0, s[98:99]
	v_mov_b32_dpp v244, v92 row_ror:8 row_mask:0xf bank_mask:0xf
	v_mov_b32_dpp v245, v93 row_ror:8 row_mask:0xf bank_mask:0xf
	v_mov_b32_dpp v246, v94 row_ror:8 row_mask:0xf bank_mask:0xf
	v_mov_b32_dpp v247, v95 row_ror:8 row_mask:0xf bank_mask:0xf
	v_mov_b32_dpp v248, v88 row_ror:8 row_mask:0xf bank_mask:0xf
	v_mov_b32_dpp v249, v89 row_ror:8 row_mask:0xf bank_mask:0xf
	v_mov_b32_dpp v250, v90 row_ror:8 row_mask:0xf bank_mask:0xf
	v_mov_b32_dpp v251, v91 row_ror:8 row_mask:0xf bank_mask:0xf
	s_nop 0
	v_cndmask_b32_e32 v92, v248, v92, vcc
	v_cndmask_b32_e32 v93, v249, v93, vcc
	v_cndmask_b32_e32 v94, v250, v94, vcc
	v_cndmask_b32_e32 v95, v251, v95, vcc
	v_cndmask_b32_e32 v88, v88, v244, vcc
	v_cndmask_b32_e32 v89, v89, v245, vcc
	v_cndmask_b32_e32 v90, v90, v246, vcc
	v_cndmask_b32_e32 v91, v91, v247, vcc
	v_mov_b32_dpp v244, v84 row_ror:8 row_mask:0xf bank_mask:0xf
	v_mov_b32_dpp v245, v85 row_ror:8 row_mask:0xf bank_mask:0xf
	v_mov_b32_dpp v246, v86 row_ror:8 row_mask:0xf bank_mask:0xf
	v_mov_b32_dpp v247, v87 row_ror:8 row_mask:0xf bank_mask:0xf
	v_mov_b32_dpp v248, v80 row_ror:8 row_mask:0xf bank_mask:0xf
	v_mov_b32_dpp v249, v81 row_ror:8 row_mask:0xf bank_mask:0xf
	v_mov_b32_dpp v250, v82 row_ror:8 row_mask:0xf bank_mask:0xf
	v_mov_b32_dpp v251, v83 row_ror:8 row_mask:0xf bank_mask:0xf
	s_nop 0
	v_cndmask_b32_e32 v84, v248, v84, vcc
	v_cndmask_b32_e32 v85, v249, v85, vcc
	v_cndmask_b32_e32 v86, v250, v86, vcc
	v_cndmask_b32_e32 v87, v251, v87, vcc
	v_cndmask_b32_e32 v80, v80, v244, vcc
	v_cndmask_b32_e32 v81, v81, v245, vcc
	v_cndmask_b32_e32 v82, v82, v246, vcc
	v_cndmask_b32_e32 v83, v83, v247, vcc
	s_waitcnt vmcnt(24)
	v_pk_add_f32 v[92:93], v[92:93], v[184:185]
	v_pk_add_f32 v[94:95], v[94:95], v[186:187]
	v_pk_add_f32 v[88:89], v[88:89], v[188:189]
	v_pk_add_f32 v[90:91], v[90:91], v[190:191]
	v_pk_add_f32 v[84:85], v[84:85], v[192:193]
	v_pk_add_f32 v[86:87], v[86:87], v[194:195]
	v_pk_add_f32 v[80:81], v[80:81], v[196:197]
	v_pk_add_f32 v[82:83], v[82:83], v[198:199]
	global_store_dwordx4 v[220:221], v[92:95], off
	global_store_dwordx4 v[222:223], v[88:91], off
	global_store_dwordx4 v[220:221], v[84:87], off offset:512
	global_store_dwordx4 v[222:223], v[80:83], off offset:512
	v_lshl_add_u64 v[220:221], v[220:221], 0, s[98:99]
	v_lshl_add_u64 v[222:223], v[222:223], 0, s[98:99]
	global_load_dwordx4 v[184:187], v[216:217], off
	global_load_dwordx4 v[188:191], v[218:219], off
	global_load_dwordx4 v[192:195], v[216:217], off offset:512
	global_load_dwordx4 v[196:199], v[218:219], off offset:512
	v_mov_b32_dpp v244, v76 row_ror:8 row_mask:0xf bank_mask:0xf
	v_mov_b32_dpp v245, v77 row_ror:8 row_mask:0xf bank_mask:0xf
	v_mov_b32_dpp v246, v78 row_ror:8 row_mask:0xf bank_mask:0xf
	v_mov_b32_dpp v247, v79 row_ror:8 row_mask:0xf bank_mask:0xf
	v_mov_b32_dpp v248, v72 row_ror:8 row_mask:0xf bank_mask:0xf
	v_mov_b32_dpp v249, v73 row_ror:8 row_mask:0xf bank_mask:0xf
	v_mov_b32_dpp v250, v74 row_ror:8 row_mask:0xf bank_mask:0xf
	v_mov_b32_dpp v251, v75 row_ror:8 row_mask:0xf bank_mask:0xf
	s_nop 0
	v_cndmask_b32_e32 v76, v248, v76, vcc
	v_cndmask_b32_e32 v77, v249, v77, vcc
	v_cndmask_b32_e32 v78, v250, v78, vcc
	v_cndmask_b32_e32 v79, v251, v79, vcc
	v_cndmask_b32_e32 v72, v72, v244, vcc
	v_cndmask_b32_e32 v73, v73, v245, vcc
	v_cndmask_b32_e32 v74, v74, v246, vcc
	v_cndmask_b32_e32 v75, v75, v247, vcc
	v_mov_b32_dpp v244, v68 row_ror:8 row_mask:0xf bank_mask:0xf
	v_mov_b32_dpp v245, v69 row_ror:8 row_mask:0xf bank_mask:0xf
	v_mov_b32_dpp v246, v70 row_ror:8 row_mask:0xf bank_mask:0xf
	v_mov_b32_dpp v247, v71 row_ror:8 row_mask:0xf bank_mask:0xf
	v_mov_b32_dpp v248, v64 row_ror:8 row_mask:0xf bank_mask:0xf
	v_mov_b32_dpp v249, v65 row_ror:8 row_mask:0xf bank_mask:0xf
	v_mov_b32_dpp v250, v66 row_ror:8 row_mask:0xf bank_mask:0xf
	v_mov_b32_dpp v251, v67 row_ror:8 row_mask:0xf bank_mask:0xf
	s_nop 0
	v_cndmask_b32_e32 v68, v248, v68, vcc
	v_cndmask_b32_e32 v69, v249, v69, vcc
	v_cndmask_b32_e32 v70, v250, v70, vcc
	v_cndmask_b32_e32 v71, v251, v71, vcc
	v_cndmask_b32_e32 v64, v64, v244, vcc
	v_cndmask_b32_e32 v65, v65, v245, vcc
	v_cndmask_b32_e32 v66, v66, v246, vcc
	v_cndmask_b32_e32 v67, v67, v247, vcc
	s_waitcnt vmcnt(28)
;     __device__ __forceinline__ void operator()(const f32x4 (&acc)[2][2][4][2], const Unit& u, int wr, int wc, int fr, int fq) const {
;         const int rbase = u.pm * 256 + wr * 64 + fr, cb = u.pn * 256 + wc * 32 + fq * 8;
; #pragma unroll
;         for (int ai = 0; ai < 2; ++ai)
; #pragma unroll
;             for (int m = 0; m < 4; ++m) { float* yr = y + (size_t)(rbase + ai * 128 + m * 16) * 1024 + cb;
; #pragma unroll
;                 for (int bj = 0; bj < 2; ++bj) { float* yp = yr + bj * 128; const f32x4 a = *(const f32x4*)yp + acc[ai][bj][m][0], b = *(const f32x4*)(yp + 4) + acc[ai][bj][m][1]; *(f32x4*)yp = a; *(f32x4*)(yp + 4) = b; }
;                 asm volatile("" ::: "memory"); }
	v_pk_add_f32 v[76:77], v[76:77], v[200:201]
	v_pk_add_f32 v[78:79], v[78:79], v[202:203]
	v_pk_add_f32 v[72:73], v[72:73], v[204:205]
	v_pk_add_f32 v[74:75], v[74:75], v[206:207]
	v_pk_add_f32 v[68:69], v[68:69], v[208:209]
	v_pk_add_f32 v[70:71], v[70:71], v[210:211]
	v_pk_add_f32 v[64:65], v[64:65], v[212:213]
	v_pk_add_f32 v[66:67], v[66:67], v[214:215]
	global_store_dwordx4 v[220:221], v[76:79], off
	global_store_dwordx4 v[222:223], v[72:75], off
	global_store_dwordx4 v[220:221], v[68:71], off offset:512
	global_store_dwordx4 v[222:223], v[64:67], off offset:512
	v_lshl_add_u64 v[220:221], v[220:221], 0, s[100:101]
	v_lshl_add_u64 v[222:223], v[222:223], 0, s[100:101]
	v_mov_b32_dpp v244, v60 row_ror:8 row_mask:0xf bank_mask:0xf
	v_mov_b32_dpp v245, v61 row_ror:8 row_mask:0xf bank_mask:0xf
	v_mov_b32_dpp v246, v62 row_ror:8 row_mask:0xf bank_mask:0xf
	v_mov_b32_dpp v247, v63 row_ror:8 row_mask:0xf bank_mask:0xf
	v_mov_b32_dpp v248, v56 row_ror:8 row_mask:0xf bank_mask:0xf
	v_mov_b32_dpp v249, v57 row_ror:8 row_mask:0xf bank_mask:0xf
	v_mov_b32_dpp v250, v58 row_ror:8 row_mask:0xf bank_mask:0xf
	v_mov_b32_dpp v251, v59 row_ror:8 row_mask:0xf bank_mask:0xf
	s_nop 0
	v_cndmask_b32_e32 v60, v248, v60, vcc
	v_cndmask_b32_e32 v61, v249, v61, vcc
	v_cndmask_b32_e32 v62, v250, v62, vcc
	v_cndmask_b32_e32 v63, v251, v63, vcc
	v_cndmask_b32_e32 v56, v56, v244, vcc
	v_cndmask_b32_e32 v57, v57, v245, vcc
	v_cndmask_b32_e32 v58, v58, v246, vcc
	v_cndmask_b32_e32 v59, v59, v247, vcc
	v_mov_b32_dpp v244, v52 row_ror:8 row_mask:0xf bank_mask:0xf
	v_mov_b32_dpp v245, v53 row_ror:8 row_mask:0xf bank_mask:0xf
	v_mov_b32_dpp v246, v54 row_ror:8 row_mask:0xf bank_mask:0xf
	v_mov_b32_dpp v247, v55 row_ror:8 row_mask:0xf bank_mask:0xf
	v_mov_b32_dpp v248, v48 row_ror:8 row_mask:0xf bank_mask:0xf
	v_mov_b32_dpp v249, v49 row_ror:8 row_mask:0xf bank_mask:0xf
	v_mov_b32_dpp v250, v50 row_ror:8 row_mask:0xf bank_mask:0xf
	v_mov_b32_dpp v251, v51 row_ror:8 row_mask:0xf bank_mask:0xf
	s_nop 0
	v_cndmask_b32_e32 v52, v248, v52, vcc
	v_cndmask_b32_e32 v53, v249, v53, vcc
	v_cndmask_b32_e32 v54, v250, v54, vcc
	v_cndmask_b32_e32 v55, v251, v55, vcc
	v_cndmask_b32_e32 v48, v48, v244, vcc
	v_cndmask_b32_e32 v49, v49, v245, vcc
	v_cndmask_b32_e32 v50, v50, v246, vcc
	v_cndmask_b32_e32 v51, v51, v247, vcc
	s_waitcnt vmcnt(28)
	v_pk_add_f32 v[60:61], v[60:61], v[228:229]
	v_pk_add_f32 v[62:63], v[62:63], v[230:231]
	v_pk_add_f32 v[56:57], v[56:57], v[232:233]
	v_pk_add_f32 v[58:59], v[58:59], v[234:235]
	v_pk_add_f32 v[52:53], v[52:53], v[236:237]
	v_pk_add_f32 v[54:55], v[54:55], v[238:239]
	v_pk_add_f32 v[48:49], v[48:49], v[240:241]
	v_pk_add_f32 v[50:51], v[50:51], v[242:243]
	global_store_dwordx4 v[220:221], v[60:63], off
	global_store_dwordx4 v[222:223], v[56:59], off
	global_store_dwordx4 v[220:221], v[52:55], off offset:512
	global_store_dwordx4 v[222:223], v[48:51], off offset:512
	v_lshl_add_u64 v[220:221], v[220:221], 0, s[98:99]
	v_lshl_add_u64 v[222:223], v[222:223], 0, s[98:99]
	v_mov_b32_dpp v244, v44 row_ror:8 row_mask:0xf bank_mask:0xf
	v_mov_b32_dpp v245, v45 row_ror:8 row_mask:0xf bank_mask:0xf
	v_mov_b32_dpp v246, v46 row_ror:8 row_mask:0xf bank_mask:0xf
	v_mov_b32_dpp v247, v47 row_ror:8 row_mask:0xf bank_mask:0xf
	v_mov_b32_dpp v248, v40 row_ror:8 row_mask:0xf bank_mask:0xf
	v_mov_b32_dpp v249, v41 row_ror:8 row_mask:0xf bank_mask:0xf
	v_mov_b32_dpp v250, v42 row_ror:8 row_mask:0xf bank_mask:0xf
	v_mov_b32_dpp v251, v43 row_ror:8 row_mask:0xf bank_mask:0xf
	s_nop 0
	v_cndmask_b32_e32 v44, v248, v44, vcc
	v_cndmask_b32_e32 v45, v249, v45, vcc
	v_cndmask_b32_e32 v46, v250, v46, vcc
	v_cndmask_b32_e32 v47, v251, v47, vcc
	v_cndmask_b32_e32 v40, v40, v244, vcc
	v_cndmask_b32_e32 v41, v41, v245, vcc
	v_cndmask_b32_e32 v42, v42, v246, vcc
	v_cndmask_b32_e32 v43, v43, v247, vcc
	v_mov_b32_dpp v244, v36 row_ror:8 row_mask:0xf bank_mask:0xf
	v_mov_b32_dpp v245, v37 row_ror:8 row_mask:0xf bank_mask:0xf
	v_mov_b32_dpp v246, v38 row_ror:8 row_mask:0xf bank_mask:0xf
	v_mov_b32_dpp v247, v39 row_ror:8 row_mask:0xf bank_mask:0xf
	v_mov_b32_dpp v248, v32 row_ror:8 row_mask:0xf bank_mask:0xf
	v_mov_b32_dpp v249, v33 row_ror:8 row_mask:0xf bank_mask:0xf
	v_mov_b32_dpp v250, v34 row_ror:8 row_mask:0xf bank_mask:0xf
	v_mov_b32_dpp v251, v35 row_ror:8 row_mask:0xf bank_mask:0xf
	s_nop 0
	v_cndmask_b32_e32 v36, v248, v36, vcc
	v_cndmask_b32_e32 v37, v249, v37, vcc
	v_cndmask_b32_e32 v38, v250, v38, vcc
	v_cndmask_b32_e32 v39, v251, v39, vcc
	v_cndmask_b32_e32 v32, v32, v244, vcc
	v_cndmask_b32_e32 v33, v33, v245, vcc
	v_cndmask_b32_e32 v34, v34, v246, vcc
	v_cndmask_b32_e32 v35, v35, v247, vcc
	s_waitcnt vmcnt(24)
;     __device__ __forceinline__ void operator()(const f32x4 (&acc)[2][2][4][2], const Unit& u, int wr, int wc, int fr, int fq) const {
;         const int rbase = u.pm * 256 + wr * 64 + fr, cb = u.pn * 256 + wc * 32 + fq * 8;
; #pragma unroll
;         for (int ai = 0; ai < 2; ++ai)
; #pragma unroll
;             for (int m = 0; m < 4; ++m) { float* yr = y + (size_t)(rbase + ai * 128 + m * 16) * 1024 + cb;
; #pragma unroll
;                 for (int bj = 0; bj < 2; ++bj) { float* yp = yr + bj * 128; const f32x4 a = *(const f32x4*)yp + acc[ai][bj][m][0], b = *(const f32x4*)(yp + 4) + acc[ai][bj][m][1]; *(f32x4*)yp = a; *(f32x4*)(yp + 4) = b; }
;                 asm volatile("" ::: "memory"); }
	v_pk_add_f32 v[44:45], v[44:45], v[152:153]
	v_pk_add_f32 v[46:47], v[46:47], v[154:155]
	v_pk_add_f32 v[40:41], v[40:41], v[156:157]
	v_pk_add_f32 v[42:43], v[42:43], v[158:159]
	v_pk_add_f32 v[36:37], v[36:37], v[160:161]
	v_pk_add_f32 v[38:39], v[38:39], v[162:163]
	v_pk_add_f32 v[32:33], v[32:33], v[164:165]
	v_pk_add_f32 v[34:35], v[34:35], v[166:167]
	global_store_dwordx4 v[220:221], v[44:47], off
	global_store_dwordx4 v[222:223], v[40:43], off
	global_store_dwordx4 v[220:221], v[36:39], off offset:512
	global_store_dwordx4 v[222:223], v[32:35], off offset:512
	v_lshl_add_u64 v[220:221], v[220:221], 0, s[98:99]
	v_lshl_add_u64 v[222:223], v[222:223], 0, s[98:99]
	v_mov_b32_dpp v244, v28 row_ror:8 row_mask:0xf bank_mask:0xf
	v_mov_b32_dpp v245, v29 row_ror:8 row_mask:0xf bank_mask:0xf
	v_mov_b32_dpp v246, v30 row_ror:8 row_mask:0xf bank_mask:0xf
	v_mov_b32_dpp v247, v31 row_ror:8 row_mask:0xf bank_mask:0xf
	v_mov_b32_dpp v248, v24 row_ror:8 row_mask:0xf bank_mask:0xf
	v_mov_b32_dpp v249, v25 row_ror:8 row_mask:0xf bank_mask:0xf
	v_mov_b32_dpp v250, v26 row_ror:8 row_mask:0xf bank_mask:0xf
	v_mov_b32_dpp v251, v27 row_ror:8 row_mask:0xf bank_mask:0xf
	s_nop 0
	v_cndmask_b32_e32 v28, v248, v28, vcc
	v_cndmask_b32_e32 v29, v249, v29, vcc
	v_cndmask_b32_e32 v30, v250, v30, vcc
	v_cndmask_b32_e32 v31, v251, v31, vcc
	v_cndmask_b32_e32 v24, v24, v244, vcc
	v_cndmask_b32_e32 v25, v25, v245, vcc
	v_cndmask_b32_e32 v26, v26, v246, vcc
	v_cndmask_b32_e32 v27, v27, v247, vcc
	v_mov_b32_dpp v244, v20 row_ror:8 row_mask:0xf bank_mask:0xf
	v_mov_b32_dpp v245, v21 row_ror:8 row_mask:0xf bank_mask:0xf
	v_mov_b32_dpp v246, v22 row_ror:8 row_mask:0xf bank_mask:0xf
	v_mov_b32_dpp v247, v23 row_ror:8 row_mask:0xf bank_mask:0xf
	v_mov_b32_dpp v248, v16 row_ror:8 row_mask:0xf bank_mask:0xf
	v_mov_b32_dpp v249, v17 row_ror:8 row_mask:0xf bank_mask:0xf
	v_mov_b32_dpp v250, v18 row_ror:8 row_mask:0xf bank_mask:0xf
	v_mov_b32_dpp v251, v19 row_ror:8 row_mask:0xf bank_mask:0xf
	s_nop 0
	v_cndmask_b32_e32 v20, v248, v20, vcc
	v_cndmask_b32_e32 v21, v249, v21, vcc
	v_cndmask_b32_e32 v22, v250, v22, vcc
	v_cndmask_b32_e32 v23, v251, v23, vcc
	v_cndmask_b32_e32 v16, v16, v244, vcc
	v_cndmask_b32_e32 v17, v17, v245, vcc
	v_cndmask_b32_e32 v18, v18, v246, vcc
	v_cndmask_b32_e32 v19, v19, v247, vcc
	s_waitcnt vmcnt(20)
	v_pk_add_f32 v[28:29], v[28:29], v[168:169]
	v_pk_add_f32 v[30:31], v[30:31], v[170:171]
	v_pk_add_f32 v[24:25], v[24:25], v[172:173]
	v_pk_add_f32 v[26:27], v[26:27], v[174:175]
	v_pk_add_f32 v[20:21], v[20:21], v[176:177]
	v_pk_add_f32 v[22:23], v[22:23], v[178:179]
	v_pk_add_f32 v[16:17], v[16:17], v[180:181]
	v_pk_add_f32 v[18:19], v[18:19], v[182:183]
	global_store_dwordx4 v[220:221], v[28:31], off
	global_store_dwordx4 v[222:223], v[24:27], off
	global_store_dwordx4 v[220:221], v[20:23], off offset:512
	global_store_dwordx4 v[222:223], v[16:19], off offset:512
	v_lshl_add_u64 v[220:221], v[220:221], 0, s[98:99]
	v_lshl_add_u64 v[222:223], v[222:223], 0, s[98:99]
	v_mov_b32_dpp v244, v12 row_ror:8 row_mask:0xf bank_mask:0xf
	v_mov_b32_dpp v245, v13 row_ror:8 row_mask:0xf bank_mask:0xf
	v_mov_b32_dpp v246, v14 row_ror:8 row_mask:0xf bank_mask:0xf
	v_mov_b32_dpp v247, v15 row_ror:8 row_mask:0xf bank_mask:0xf
	v_mov_b32_dpp v248, v8 row_ror:8 row_mask:0xf bank_mask:0xf
	v_mov_b32_dpp v249, v9 row_ror:8 row_mask:0xf bank_mask:0xf
	v_mov_b32_dpp v250, v10 row_ror:8 row_mask:0xf bank_mask:0xf
	v_mov_b32_dpp v251, v11 row_ror:8 row_mask:0xf bank_mask:0xf
	s_nop 0
	v_cndmask_b32_e32 v12, v248, v12, vcc
	v_cndmask_b32_e32 v13, v249, v13, vcc
	v_cndmask_b32_e32 v14, v250, v14, vcc
	v_cndmask_b32_e32 v15, v251, v15, vcc
	v_cndmask_b32_e32 v8, v8, v244, vcc
	v_cndmask_b32_e32 v9, v9, v245, vcc
	v_cndmask_b32_e32 v10, v10, v246, vcc
	v_cndmask_b32_e32 v11, v11, v247, vcc
	v_mov_b32_dpp v244, v4 row_ror:8 row_mask:0xf bank_mask:0xf
	v_mov_b32_dpp v245, v5 row_ror:8 row_mask:0xf bank_mask:0xf
	v_mov_b32_dpp v246, v6 row_ror:8 row_mask:0xf bank_mask:0xf
	v_mov_b32_dpp v247, v7 row_ror:8 row_mask:0xf bank_mask:0xf
	v_mov_b32_dpp v248, v0 row_ror:8 row_mask:0xf bank_mask:0xf
	v_mov_b32_dpp v249, v1 row_ror:8 row_mask:0xf bank_mask:0xf
	v_mov_b32_dpp v250, v2 row_ror:8 row_mask:0xf bank_mask:0xf
	v_mov_b32_dpp v251, v3 row_ror:8 row_mask:0xf bank_mask:0xf
	s_nop 0
	v_cndmask_b32_e32 v4, v248, v4, vcc
	v_cndmask_b32_e32 v5, v249, v5, vcc
	v_cndmask_b32_e32 v6, v250, v6, vcc
	v_cndmask_b32_e32 v7, v251, v7, vcc
	v_cndmask_b32_e32 v0, v0, v244, vcc
	v_cndmask_b32_e32 v1, v1, v245, vcc
	v_cndmask_b32_e32 v2, v2, v246, vcc
	v_cndmask_b32_e32 v3, v3, v247, vcc
	s_waitcnt vmcnt(16)
	v_pk_add_f32 v[12:13], v[12:13], v[184:185]
	v_pk_add_f32 v[14:15], v[14:15], v[186:187]
	v_pk_add_f32 v[8:9], v[8:9], v[188:189]
	v_pk_add_f32 v[10:11], v[10:11], v[190:191]
	v_pk_add_f32 v[4:5], v[4:5], v[192:193]
	v_pk_add_f32 v[6:7], v[6:7], v[194:195]
	v_pk_add_f32 v[0:1], v[0:1], v[196:197]
	v_pk_add_f32 v[2:3], v[2:3], v[198:199]
	global_store_dwordx4 v[220:221], v[12:15], off
	global_store_dwordx4 v[222:223], v[8:11], off
	global_store_dwordx4 v[220:221], v[4:7], off offset:512
	global_store_dwordx4 v[222:223], v[0:3], off offset:512
	s_andn2_b64 vcc, exec, s[0:1]
	s_mov_b64 s[0:1], -1
	s_cbranch_vccnz .LBB0_2132
	s_andn2_b64 vcc, exec, s[4:5]
	s_cbranch_vccnz .LBB0_2131
	s_barrier
	s_branch .LBB0_2131
